# unit-order division shortcut extended to mixer-in and mixer-out GEMM unit headers
# baseline (speedup 1.0000x reference)
;     __host__ __device__ bool next(int i, Unit& u) const {
;         const long L = (long)i * G + c; if (L >= nwg) return false;
;         int wgid = (int)L; { const int q = nwg / NXCD, r = nwg % NXCD, xcd = wgid % NXCD, off = wgid / NXCD; wgid = (xcd < r ? xcd * (q + 1) : r * (q + 1) + (xcd - r) * q) + off; }
;         const int nig = WGM * nN, gid = wgid / nig, fm = gid * WGM, gsz = (nM - fm) < WGM ? (nM - fm) : WGM;
;         u.pm = fm + ((wgid % nig) % gsz); u.pn = (wgid % nig) / gsz; return true;
;     }
.LBB0_394:
	s_ashr_i32 s20, s22, 3
	s_add_i32 s20, s24, s20
	s_ashr_i32 s21, s20, 31
	s_lshr_b32 s21, s21, 25
	s_add_i32 s21, s20, s21
	s_ashr_i32 s22, s21, 7
	s_lshl_b32 s22, s22, 3
	s_sub_i32 s23, 64, s22
	s_min_i32 s23, s23, 8
	s_and_b32 s21, s21, 0xffffff80
	s_sub_i32 s21, s20, s21
	s_ashr_i32 s20, s21, 3
	s_and_b32 s21, s21, 7
	s_add_i32 s22, s22, s21

;     __host__ __device__ bool next(int i, Unit& u) const {
;         const long L = (long)i * G + c; if (L >= nwg) return false;
;         int wgid = (int)L; { const int q = nwg / NXCD, r = nwg % NXCD, xcd = wgid % NXCD, off = wgid / NXCD; wgid = (xcd < r ? xcd * (q + 1) : r * (q + 1) + (xcd - r) * q) + off; }
;         const int nig = WGM * nN, gid = wgid / nig, fm = gid * WGM, gsz = (nM - fm) < WGM ? (nM - fm) : WGM;
;         u.pm = fm + ((wgid % nig) % gsz); u.pn = (wgid % nig) / gsz; return true;
;     }
.LBB0_816:
	s_ashr_i32 s18, s20, 3
	s_add_i32 s18, s22, s18
	s_ashr_i32 s19, s18, 31
	s_lshr_b32 s19, s19, 27
	s_add_i32 s19, s18, s19
	s_ashr_i32 s20, s19, 5
	s_lshl_b32 s20, s20, 3
	s_sub_i32 s21, 64, s20
	s_min_i32 s21, s21, 8
	s_andn2_b32 s19, s19, 31
	s_sub_i32 s19, s18, s19
	s_ashr_i32 s18, s19, 3
	s_and_b32 s19, s19, 7
	s_add_i32 s20, s20, s19

;     __host__ __device__ bool next(int i, Unit& u) const {
;         const long L = (long)i * G + c; if (L >= nwg) return false;
;         int wgid = (int)L; { const int q = nwg / NXCD, r = nwg % NXCD, xcd = wgid % NXCD, off = wgid / NXCD; wgid = (xcd < r ? xcd * (q + 1) : r * (q + 1) + (xcd - r) * q) + off; }
;         const int nig = WGM * nN, gid = wgid / nig, fm = gid * WGM, gsz = (nM - fm) < WGM ? (nM - fm) : WGM;
;         u.pm = fm + ((wgid % nig) % gsz); u.pn = (wgid % nig) / gsz; return true;
;     }
.LBB0_903:
	s_ashr_i32 s18, s20, 3
	s_add_i32 s18, s24, s18
	s_ashr_i32 s19, s18, 31
	s_lshr_b32 s19, s19, 26
	s_add_i32 s19, s18, s19
	s_ashr_i32 s20, s19, 6
	s_lshl_b32 s20, s20, 3
	s_sub_i32 s21, 64, s20
	s_min_i32 s21, s21, 8
	s_andn2_b32 s19, s19, 63
	s_sub_i32 s19, s18, s19
	s_ashr_i32 s18, s19, 3
	s_and_b32 s19, s19, 7
	s_add_i32 s20, s20, s19

;     __host__ __device__ bool next(int i, Unit& u) const {
;         const long L = (long)i * G + c; if (L >= nwg) return false;
;         int wgid = (int)L; { const int q = nwg / NXCD, r = nwg % NXCD, xcd = wgid % NXCD, off = wgid / NXCD; wgid = (xcd < r ? xcd * (q + 1) : r * (q + 1) + (xcd - r) * q) + off; }
;         const int nig = WGM * nN, gid = wgid / nig, fm = gid * WGM, gsz = (nM - fm) < WGM ? (nM - fm) : WGM;
;         u.pm = fm + ((wgid % nig) % gsz); u.pn = (wgid % nig) / gsz; return true;
;     }
.LBB0_1628:
	s_ashr_i32 s16, s18, 3
	s_add_i32 s16, s22, s16
	s_ashr_i32 s17, s16, 31
	s_lshr_b32 s17, s17, 26
	s_add_i32 s17, s16, s17
	s_ashr_i32 s18, s17, 6
	s_lshl_b32 s18, s18, 3
	s_sub_i32 s19, 64, s18
	s_min_i32 s19, s19, 8
	s_andn2_b32 s17, s17, 63
	s_sub_i32 s17, s16, s17
	s_ashr_i32 s16, s17, 3
	s_and_b32 s17, s17, 7
	s_add_i32 s18, s18, s17
